# speedup vs baseline: 1.0105x; 1.0059x over previous
; __device__ __forceinline__ unsigned cvt_pk(float lo, float hi) { unsigned r; asm("v_cvt_pk_bf16_f32 %0, %1, %2" : "=v"(r) : "v"(lo), "v"(hi)); return r; }
; __device__ __forceinline__ void p0_prologue(unsigned char* lds, const Params& p, int G, int bid) {
;     ...
;     { const f32x4* s = (const f32x4*)p.in[0]; u32x2* d = (u32x2*)XB; for (int i = gt; i < MP * D / 4; i += GT) { const f32x4 v = __builtin_nontemporal_load(s + i); u32x2 w; w.x = cvt_pk(v[0], v[1]); w.y = cvt_pk(v[2], v[3]); d[i] = w; } }
.Lmy_xcvt8:
	s_mul_i32 s98, s0, 7
	v_add_u32_e32 v7, s98, v6
	v_cmp_ge_i32_e32 vcc, s1, v7
	s_xor_b64 s[100:101], vcc, exec
	s_cmp_eq_u64 s[100:101], 0
	s_cbranch_scc0 .LBB0_528
	global_load_dwordx4 v[100:103], v[0:1], off nt
	v_lshl_add_u64 v[0:1], v[0:1], 0, s[4:5]
	global_load_dwordx4 v[104:107], v[0:1], off nt
	v_lshl_add_u64 v[0:1], v[0:1], 0, s[4:5]
	global_load_dwordx4 v[108:111], v[0:1], off nt
	v_lshl_add_u64 v[0:1], v[0:1], 0, s[4:5]
	global_load_dwordx4 v[112:115], v[0:1], off nt
	v_lshl_add_u64 v[0:1], v[0:1], 0, s[4:5]
	global_load_dwordx4 v[116:119], v[0:1], off nt
	v_lshl_add_u64 v[0:1], v[0:1], 0, s[4:5]
	global_load_dwordx4 v[120:123], v[0:1], off nt
	v_lshl_add_u64 v[0:1], v[0:1], 0, s[4:5]
	global_load_dwordx4 v[124:127], v[0:1], off nt
	v_lshl_add_u64 v[0:1], v[0:1], 0, s[4:5]
	global_load_dwordx4 v[128:131], v[0:1], off nt
	v_lshl_add_u64 v[0:1], v[0:1], 0, s[4:5]
	s_waitcnt vmcnt(0)
	v_cvt_pk_bf16_f32 v100, v100, v101
	v_cvt_pk_bf16_f32 v101, v102, v103
	global_store_dwordx2 v[2:3], v[100:101], off
	v_lshl_add_u64 v[2:3], v[2:3], 0, s[8:9]
	v_cvt_pk_bf16_f32 v104, v104, v105
	v_cvt_pk_bf16_f32 v105, v106, v107
	global_store_dwordx2 v[2:3], v[104:105], off
	v_lshl_add_u64 v[2:3], v[2:3], 0, s[8:9]
	v_cvt_pk_bf16_f32 v108, v108, v109
	v_cvt_pk_bf16_f32 v109, v110, v111
	global_store_dwordx2 v[2:3], v[108:109], off
	v_lshl_add_u64 v[2:3], v[2:3], 0, s[8:9]
	v_cvt_pk_bf16_f32 v112, v112, v113
	v_cvt_pk_bf16_f32 v113, v114, v115
	global_store_dwordx2 v[2:3], v[112:113], off
	v_lshl_add_u64 v[2:3], v[2:3], 0, s[8:9]
	v_cvt_pk_bf16_f32 v116, v116, v117
	v_cvt_pk_bf16_f32 v117, v118, v119
	global_store_dwordx2 v[2:3], v[116:117], off
	v_lshl_add_u64 v[2:3], v[2:3], 0, s[8:9]
	v_cvt_pk_bf16_f32 v120, v120, v121
	v_cvt_pk_bf16_f32 v121, v122, v123
	global_store_dwordx2 v[2:3], v[120:121], off
	v_lshl_add_u64 v[2:3], v[2:3], 0, s[8:9]
	v_cvt_pk_bf16_f32 v124, v124, v125
	v_cvt_pk_bf16_f32 v125, v126, v127
	global_store_dwordx2 v[2:3], v[124:125], off
	v_lshl_add_u64 v[2:3], v[2:3], 0, s[8:9]
	v_cvt_pk_bf16_f32 v128, v128, v129
	v_cvt_pk_bf16_f32 v129, v130, v131
	global_store_dwordx2 v[2:3], v[128:129], off
	v_lshl_add_u64 v[2:3], v[2:3], 0, s[8:9]
	s_lshl_b32 s99, s0, 3
	v_add_u32_e32 v6, s99, v6
	v_cmp_ge_i32_e32 vcc, s1, v6
	s_and_b64 exec, exec, vcc
	s_cbranch_execnz .Lmy_xcvt8
	s_branch .LBB0_529
